# grid barrier: non-leader workgroups poll the cross-XCD release generation directly (one relay hop less)
# speedup vs baseline: 1.0038x; 1.0004x over previous
; DI int tidx() { int t = threadIdx.x; asm volatile("" : "+v"(t)); return t; }
; __device__ __forceinline__ unsigned xb_ld(unsigned* p)              { return __hip_atomic_load(p, __ATOMIC_RELAXED, __HIP_MEMORY_SCOPE_AGENT); }
; __device__ __forceinline__ unsigned xb_add(unsigned* p, unsigned v) { return __hip_atomic_fetch_add(p, v, __ATOMIC_RELAXED, __HIP_MEMORY_SCOPE_AGENT); }
; #define XB_SPIN(cond, bar) do { unsigned _sp = 0; while (cond) { __builtin_amdgcn_s_sleep(1); \
;     if ((++_sp & 255u) == 0u) { if (xb_ld(&(bar)[XB_TMO])) break; if (_sp > XB_SPIN_CAP) { atomicAdd(&(bar)[XB_TMO], 1u); break; } } } } while (0)
; __device__ __forceinline__ void xcd_barrier(const XcdBarrier& b) {
;     asm volatile("s_waitcnt vmcnt(0)" ::: "memory");
;     __syncthreads();
;     if (tidx() == 0) {
;         unsigned* bar = b.bar; asm volatile("" : "+s"(bar));
;         __builtin_amdgcn_s_waitcnt(0);
;         unsigned nloc = b.st[0], nx = b.st[1];
;         if (nloc == 0u) { xcd_barrier_complete(bar, b.x, nloc, nx); b.st[0] = nloc; b.st[1] = nx; }
;         const unsigned old = xb_add(&bar[XB_XSUB(b.x)], 1u);
;         const unsigned gen = old / nloc;
;         if (old + 1u == (gen + 1u) * nloc) {
;             __builtin_amdgcn_fence(__ATOMIC_RELEASE, "agent");
;             asm volatile("s_waitcnt vmcnt(0)" ::: "memory");
;             const unsigned og = xb_add(&bar[XB_TOP], 1u);
;             const unsigned tg = og / nx;
;             if (og + 1u == (tg + 1u) * nx) xb_add(&bar[XB_TOPGEN], 1u);
;             else XB_SPIN(xb_ld(&bar[XB_TOPGEN]) == tg, bar);
;             __builtin_amdgcn_fence(__ATOMIC_ACQUIRE, "agent");
;             xb_add(&bar[XB_XGEN(b.x)], 1u);
;             asm volatile("s_waitcnt vmcnt(0)" ::: "memory");
;         } else {
;             XB_SPIN(xb_ld(&bar[XB_XGEN(b.x)]) == gen, bar);
;             __builtin_amdgcn_fence(__ATOMIC_ACQUIRE, "agent");
;             asm volatile("s_waitcnt vmcnt(0)" ::: "memory");
;         }
.LBB0_192:
	v_readlane_b32 s0, v252, 41
	s_lshl_b32 s0, s0, 2
	s_add_u32 s48, s4, s0
	s_addc_u32 s10, s5, 0
	v_mov_b32_e32 v3, s48
	v_add_co_u32_e32 v4, vcc, 0x1000, v3
	v_mov_b32_e32 v3, s10
	s_nop 0
	v_addc_co_u32_e32 v5, vcc, 0, v3, vcc
	flat_atomic_add v3, v[4:5], v223 offset:1024 sc0
	v_cvt_f32_u32_e32 v4, v2
	v_sub_u32_e32 v5, 0, v2
	v_rcp_iflag_f32_e32 v4, v4
	s_nop 0
	v_mul_f32_e32 v4, 0x4f7ffffe, v4
	v_cvt_u32_f32_e32 v4, v4
	v_mul_lo_u32 v5, v5, v4
	v_mul_hi_u32 v5, v4, v5
	v_add_u32_e32 v4, v4, v5
	s_waitcnt vmcnt(0) lgkmcnt(0)
	v_mul_hi_u32 v4, v3, v4
	v_mul_lo_u32 v5, v4, v2
	v_add_u32_e32 v6, 1, v3
	v_sub_u32_e32 v3, v3, v5
	v_add_u32_e32 v7, 1, v4
	v_sub_u32_e32 v5, v3, v2
	v_cmp_ge_u32_e32 vcc, v3, v2
	s_nop 1
	v_cndmask_b32_e32 v4, v4, v7, vcc
	v_cndmask_b32_e32 v3, v3, v5, vcc
	v_add_u32_e32 v5, 1, v4
	v_cmp_ge_u32_e32 vcc, v3, v2
	s_nop 1
	v_cndmask_b32_e32 v3, v4, v5, vcc
	v_mad_u64_u32 v[4:5], s[6:7], v2, v3, v[2:3]
	v_cmp_ne_u32_e32 vcc, v6, v4
	s_and_saveexec_b64 s[6:7], vcc
	s_xor_b64 s[34:35], exec, s[6:7]
	s_cbranch_execz .LBB0_205
	s_add_u32 s20, s4, 0x3500
	s_addc_u32 s21, s5, 0
	v_mov_b64_e32 v[4:5], s[20:21]
	flat_load_dword v0, v[4:5] sc1
	s_waitcnt vmcnt(0) lgkmcnt(0)
	v_cmp_eq_u32_e32 vcc, v0, v3
	s_and_saveexec_b64 s[22:23], vcc
	s_cbranch_execz .LBB0_204
	s_mov_b32 s49, 1
	s_mov_b64 s[6:7], 0
	s_branch .LBB0_196

; __device__ __forceinline__ unsigned xb_ld(unsigned* p)              { return __hip_atomic_load(p, __ATOMIC_RELAXED, __HIP_MEMORY_SCOPE_AGENT); }
; __device__ __forceinline__ unsigned xb_add(unsigned* p, unsigned v) { return __hip_atomic_fetch_add(p, v, __ATOMIC_RELAXED, __HIP_MEMORY_SCOPE_AGENT); }
; #define XB_SPIN(cond, bar) do { unsigned _sp = 0; while (cond) { __builtin_amdgcn_s_sleep(1); \
;     if ((++_sp & 255u) == 0u) { if (xb_ld(&(bar)[XB_TMO])) break; if (_sp > XB_SPIN_CAP) { atomicAdd(&(bar)[XB_TMO], 1u); break; } } } } while (0)
; __device__ __forceinline__ void xcd_barrier(const XcdBarrier& b) {
;     ...
;         const unsigned old = xb_add(&bar[XB_XSUB(b.x)], 1u);
;         const unsigned gen = old / nloc;
;         if (old + 1u == (gen + 1u) * nloc) {
;             __builtin_amdgcn_fence(__ATOMIC_RELEASE, "agent");
;             asm volatile("s_waitcnt vmcnt(0)" ::: "memory");
;             const unsigned og = xb_add(&bar[XB_TOP], 1u);
;             const unsigned tg = og / nx;
;             if (og + 1u == (tg + 1u) * nx) xb_add(&bar[XB_TOPGEN], 1u);
;             else XB_SPIN(xb_ld(&bar[XB_TOPGEN]) == tg, bar);
;             __builtin_amdgcn_fence(__ATOMIC_ACQUIRE, "agent");
;             xb_add(&bar[XB_XGEN(b.x)], 1u);
;             asm volatile("s_waitcnt vmcnt(0)" ::: "memory");
;         } else {
;             XB_SPIN(xb_ld(&bar[XB_XGEN(b.x)]) == gen, bar);
;             __builtin_amdgcn_fence(__ATOMIC_ACQUIRE, "agent");
;             asm volatile("s_waitcnt vmcnt(0)" ::: "memory");
;         }
.LBB0_290:
	v_readlane_b32 s0, v252, 41
	s_lshl_b32 s0, s0, 2
	s_add_u32 s48, s4, s0
	s_addc_u32 s10, s5, 0
	v_mov_b32_e32 v3, s48
	v_add_co_u32_e32 v4, vcc, 0x1000, v3
	v_mov_b32_e32 v3, s10
	s_nop 0
	v_addc_co_u32_e32 v5, vcc, 0, v3, vcc
	flat_atomic_add v4, v[4:5], v223 offset:1024 sc0
	v_cvt_f32_u32_e32 v3, v2
	v_sub_u32_e32 v5, 0, v2
	v_rcp_iflag_f32_e32 v3, v3
	s_nop 0
	v_mul_f32_e32 v3, 0x4f7ffffe, v3
	v_cvt_u32_f32_e32 v3, v3
	v_mul_lo_u32 v5, v5, v3
	v_mul_hi_u32 v5, v3, v5
	v_add_u32_e32 v3, v3, v5
	s_waitcnt vmcnt(0) lgkmcnt(0)
	v_mul_hi_u32 v3, v4, v3
	v_mul_lo_u32 v5, v3, v2
	v_sub_u32_e32 v5, v4, v5
	v_cmp_ge_u32_e32 vcc, v5, v2
	v_add_u32_e32 v6, 1, v3
	s_nop 0
	v_cndmask_b32_e32 v3, v3, v6, vcc
	v_sub_u32_e32 v6, v5, v2
	v_cndmask_b32_e32 v5, v5, v6, vcc
	v_cmp_ge_u32_e32 vcc, v5, v2
	v_add_u32_e32 v5, 1, v3
	v_add_u32_e32 v6, 1, v4
	v_cndmask_b32_e32 v3, v3, v5, vcc
	v_mad_u64_u32 v[4:5], s[6:7], v2, v3, v[2:3]
	v_cmp_ne_u32_e32 vcc, v6, v4
	s_and_saveexec_b64 s[6:7], vcc
	s_xor_b64 s[34:35], exec, s[6:7]
	s_cbranch_execz .LBB0_303
	s_add_u32 s20, s4, 0x3500
	s_addc_u32 s21, s5, 0
	v_mov_b64_e32 v[4:5], s[20:21]
	flat_load_dword v0, v[4:5] sc1
	s_waitcnt vmcnt(0) lgkmcnt(0)
	v_cmp_eq_u32_e32 vcc, v0, v3
	s_and_saveexec_b64 s[22:23], vcc
	s_cbranch_execz .LBB0_302
	s_mov_b32 s49, 1
	s_mov_b64 s[6:7], 0
	s_branch .LBB0_294

; __device__ __forceinline__ unsigned xb_ld(unsigned* p)              { return __hip_atomic_load(p, __ATOMIC_RELAXED, __HIP_MEMORY_SCOPE_AGENT); }
; __device__ __forceinline__ unsigned xb_add(unsigned* p, unsigned v) { return __hip_atomic_fetch_add(p, v, __ATOMIC_RELAXED, __HIP_MEMORY_SCOPE_AGENT); }
; #define XB_SPIN(cond, bar) do { unsigned _sp = 0; while (cond) { __builtin_amdgcn_s_sleep(1); \
;     if ((++_sp & 255u) == 0u) { if (xb_ld(&(bar)[XB_TMO])) break; if (_sp > XB_SPIN_CAP) { atomicAdd(&(bar)[XB_TMO], 1u); break; } } } } while (0)
; __device__ __forceinline__ void xcd_barrier(const XcdBarrier& b) {
;     ...
;         const unsigned old = xb_add(&bar[XB_XSUB(b.x)], 1u);
;         const unsigned gen = old / nloc;
;         if (old + 1u == (gen + 1u) * nloc) {
;             __builtin_amdgcn_fence(__ATOMIC_RELEASE, "agent");
;             asm volatile("s_waitcnt vmcnt(0)" ::: "memory");
;             const unsigned og = xb_add(&bar[XB_TOP], 1u);
;             const unsigned tg = og / nx;
;             if (og + 1u == (tg + 1u) * nx) xb_add(&bar[XB_TOPGEN], 1u);
;             else XB_SPIN(xb_ld(&bar[XB_TOPGEN]) == tg, bar);
;             __builtin_amdgcn_fence(__ATOMIC_ACQUIRE, "agent");
;             xb_add(&bar[XB_XGEN(b.x)], 1u);
;             asm volatile("s_waitcnt vmcnt(0)" ::: "memory");
;         } else {
;             XB_SPIN(xb_ld(&bar[XB_XGEN(b.x)]) == gen, bar);
;             __builtin_amdgcn_fence(__ATOMIC_ACQUIRE, "agent");
;             asm volatile("s_waitcnt vmcnt(0)" ::: "memory");
;         }
.LBB0_459:
	v_readlane_b32 s0, v252, 41
	s_lshl_b32 s0, s0, 2
	s_add_u32 s44, s4, s0
	s_addc_u32 s10, s5, 0
	v_mov_b32_e32 v3, s44
	v_add_co_u32_e32 v4, vcc, 0x1000, v3
	v_mov_b32_e32 v3, s10
	s_nop 0
	v_addc_co_u32_e32 v5, vcc, 0, v3, vcc
	flat_atomic_add v4, v[4:5], v223 offset:1024 sc0
	v_cvt_f32_u32_e32 v3, v2
	v_sub_u32_e32 v5, 0, v2
	v_rcp_iflag_f32_e32 v3, v3
	s_nop 0
	v_mul_f32_e32 v3, 0x4f7ffffe, v3
	v_cvt_u32_f32_e32 v3, v3
	v_mul_lo_u32 v5, v5, v3
	v_mul_hi_u32 v5, v3, v5
	v_add_u32_e32 v3, v3, v5
	s_waitcnt vmcnt(0) lgkmcnt(0)
	v_mul_hi_u32 v3, v4, v3
	v_mul_lo_u32 v5, v3, v2
	v_sub_u32_e32 v5, v4, v5
	v_cmp_ge_u32_e32 vcc, v5, v2
	v_add_u32_e32 v6, 1, v3
	s_nop 0
	v_cndmask_b32_e32 v3, v3, v6, vcc
	v_sub_u32_e32 v6, v5, v2
	v_cndmask_b32_e32 v5, v5, v6, vcc
	v_cmp_ge_u32_e32 vcc, v5, v2
	v_add_u32_e32 v5, 1, v3
	v_add_u32_e32 v6, 1, v4
	v_cndmask_b32_e32 v3, v3, v5, vcc
	v_mad_u64_u32 v[4:5], s[6:7], v2, v3, v[2:3]
	v_cmp_ne_u32_e32 vcc, v6, v4
	s_and_saveexec_b64 s[6:7], vcc
	s_xor_b64 s[8:9], exec, s[6:7]
	s_cbranch_execz .LBB0_472
	s_add_u32 s20, s4, 0x3500
	s_addc_u32 s21, s5, 0
	v_mov_b64_e32 v[4:5], s[20:21]
	flat_load_dword v0, v[4:5] sc1
	s_waitcnt vmcnt(0) lgkmcnt(0)
	v_cmp_eq_u32_e32 vcc, v0, v3
	s_and_saveexec_b64 s[12:13], vcc
	s_cbranch_execz .LBB0_471
	s_mov_b32 s45, 1
	s_mov_b64 s[6:7], 0
	s_branch .LBB0_463

; __device__ __forceinline__ unsigned xb_ld(unsigned* p)              { return __hip_atomic_load(p, __ATOMIC_RELAXED, __HIP_MEMORY_SCOPE_AGENT); }
; __device__ __forceinline__ unsigned xb_add(unsigned* p, unsigned v) { return __hip_atomic_fetch_add(p, v, __ATOMIC_RELAXED, __HIP_MEMORY_SCOPE_AGENT); }
; #define XB_SPIN(cond, bar) do { unsigned _sp = 0; while (cond) { __builtin_amdgcn_s_sleep(1); \
;     if ((++_sp & 255u) == 0u) { if (xb_ld(&(bar)[XB_TMO])) break; if (_sp > XB_SPIN_CAP) { atomicAdd(&(bar)[XB_TMO], 1u); break; } } } } while (0)
; __device__ __forceinline__ void xcd_barrier(const XcdBarrier& b) {
;     ...
;         const unsigned old = xb_add(&bar[XB_XSUB(b.x)], 1u);
;         const unsigned gen = old / nloc;
;         if (old + 1u == (gen + 1u) * nloc) {
;             __builtin_amdgcn_fence(__ATOMIC_RELEASE, "agent");
;             asm volatile("s_waitcnt vmcnt(0)" ::: "memory");
;             const unsigned og = xb_add(&bar[XB_TOP], 1u);
;             const unsigned tg = og / nx;
;             if (og + 1u == (tg + 1u) * nx) xb_add(&bar[XB_TOPGEN], 1u);
;             else XB_SPIN(xb_ld(&bar[XB_TOPGEN]) == tg, bar);
;             __builtin_amdgcn_fence(__ATOMIC_ACQUIRE, "agent");
;             xb_add(&bar[XB_XGEN(b.x)], 1u);
;             asm volatile("s_waitcnt vmcnt(0)" ::: "memory");
;         } else {
;             XB_SPIN(xb_ld(&bar[XB_XGEN(b.x)]) == gen, bar);
;             __builtin_amdgcn_fence(__ATOMIC_ACQUIRE, "agent");
;             asm volatile("s_waitcnt vmcnt(0)" ::: "memory");
;         }
.LBB0_831:
	v_readlane_b32 s0, v252, 41
	s_lshl_b32 s0, s0, 2
	s_add_u32 s44, s4, s0
	s_addc_u32 s10, s5, 0
	v_mov_b32_e32 v3, s44
	v_add_co_u32_e32 v4, vcc, 0x1000, v3
	v_mov_b32_e32 v3, s10
	s_nop 0
	v_addc_co_u32_e32 v5, vcc, 0, v3, vcc
	flat_atomic_add v4, v[4:5], v223 offset:1024 sc0
	v_cvt_f32_u32_e32 v3, v2
	v_sub_u32_e32 v5, 0, v2
	v_rcp_iflag_f32_e32 v3, v3
	s_nop 0
	v_mul_f32_e32 v3, 0x4f7ffffe, v3
	v_cvt_u32_f32_e32 v3, v3
	v_mul_lo_u32 v5, v5, v3
	v_mul_hi_u32 v5, v3, v5
	v_add_u32_e32 v3, v3, v5
	s_waitcnt vmcnt(0) lgkmcnt(0)
	v_mul_hi_u32 v3, v4, v3
	v_mul_lo_u32 v5, v3, v2
	v_sub_u32_e32 v5, v4, v5
	v_cmp_ge_u32_e32 vcc, v5, v2
	v_add_u32_e32 v6, 1, v3
	s_nop 0
	v_cndmask_b32_e32 v3, v3, v6, vcc
	v_sub_u32_e32 v6, v5, v2
	v_cndmask_b32_e32 v5, v5, v6, vcc
	v_cmp_ge_u32_e32 vcc, v5, v2
	v_add_u32_e32 v5, 1, v3
	v_add_u32_e32 v6, 1, v4
	v_cndmask_b32_e32 v3, v3, v5, vcc
	v_mad_u64_u32 v[4:5], s[0:1], v2, v3, v[2:3]
	v_cmp_ne_u32_e32 vcc, v6, v4
	s_and_saveexec_b64 s[0:1], vcc
	s_xor_b64 s[8:9], exec, s[0:1]
	s_cbranch_execz .LBB0_844
	s_add_u32 s20, s4, 0x3500
	s_addc_u32 s21, s5, 0
	v_mov_b64_e32 v[4:5], s[20:21]
	flat_load_dword v0, v[4:5] sc1
	s_waitcnt vmcnt(0) lgkmcnt(0)
	v_cmp_eq_u32_e32 vcc, v0, v3
	s_and_saveexec_b64 s[12:13], vcc
	s_cbranch_execz .LBB0_843
	s_mov_b32 s45, 1
	s_mov_b64 s[6:7], 0
	s_branch .LBB0_835
